# P0: XB bf16 rows stored write-through (sc1) so the first grid barrier has less dirty L2 to flush
# baseline (speedup 1.0000x reference)
; __device__ __forceinline__ unsigned cvt_pk_bf16(float lo, float hi) { unsigned r; asm volatile("v_cvt_pk_bf16_f32 %0, %1, %2" : "=v"(r) : "v"(lo), "v"(hi)); return r; }
;     ...
;     for (int row = gw; row < pg8::MROWS; row += NGW) {
;         const f32x4* xr = (const f32x4*)(x + (size_t)row * 2048) + lane; u32x2* xo = (u32x2*)(XB + (size_t)row * 2048) + lane; float ss = 0.f;
; #pragma unroll
;         for (int j = 0; j < 8; ++j) { const f32x4 v = xr[64 * j]; ss += (v[0] * v[0] + v[1] * v[1]) + (v[2] * v[2] + v[3] * v[3]); u32x2 o; o.x = cvt_pk_bf16(v[0], v[1]); o.y = cvt_pk_bf16(v[2], v[3]); xo[64 * j] = o; }
;         ss = wave_sum(ss); if (lane < 8) SSQ[(size_t)lane * pg8::MROWS + row] = lane == 0 ? ss : 0.f;
;     }
.LBB0_56:
	v_lshl_add_u64 v[22:23], s[92:93], 0, v[6:7]
	v_add_co_u32_e64 v50, s[6:7], s13, v22
	s_waitcnt lgkmcnt(0)
	s_nop 1
	v_addc_co_u32_e64 v51, s[6:7], 0, v23, s[6:7]
	global_load_dwordx4 v[18:21], v[4:5], off offset:-4096
	global_load_dwordx4 v[22:25], v[4:5], off offset:-3072
	global_load_dwordx4 v[26:29], v[4:5], off offset:-2048
	global_load_dwordx4 v[30:33], v[4:5], off offset:-1024
	global_load_dwordx4 v[34:37], v[4:5], off
	global_load_dwordx4 v[38:41], v[4:5], off offset:1024
	global_load_dwordx4 v[42:45], v[4:5], off offset:2048
	global_load_dwordx4 v[46:49], v[4:5], off offset:3072
	s_waitcnt vmcnt(0)
	v_cvt_pk_bf16_f32 v52, v18, v19
	v_cvt_pk_bf16_f32 v53, v20, v21
	global_store_dwordx2 v[50:51], v[52:53], off sc1
	v_cvt_pk_bf16_f32 v54, v22, v23
	v_cvt_pk_bf16_f32 v55, v24, v25
	global_store_dwordx2 v[50:51], v[54:55], off offset:512 sc1
	v_cvt_pk_bf16_f32 v56, v26, v27
	v_cvt_pk_bf16_f32 v57, v28, v29
	global_store_dwordx2 v[50:51], v[56:57], off offset:1024 sc1
	v_cvt_pk_bf16_f32 v58, v30, v31
	v_cvt_pk_bf16_f32 v59, v32, v33
	global_store_dwordx2 v[50:51], v[58:59], off offset:1536 sc1
	v_cvt_pk_bf16_f32 v60, v34, v35
	v_cvt_pk_bf16_f32 v61, v36, v37
	global_store_dwordx2 v[50:51], v[60:61], off offset:2048 sc1
	v_cvt_pk_bf16_f32 v62, v38, v39
	v_cvt_pk_bf16_f32 v63, v40, v41
	global_store_dwordx2 v[50:51], v[62:63], off offset:2560 sc1
	v_cvt_pk_bf16_f32 v64, v42, v43
	v_cvt_pk_bf16_f32 v65, v44, v45
	global_store_dwordx2 v[50:51], v[64:65], off offset:3072 sc1
	v_cmp_lt_i32_e64 s[6:7], v11, v10
	v_mul_f32_e32 v19, v19, v19
	v_mul_f32_e32 v21, v21, v21
	v_fmac_f32_e32 v19, v18, v18
	v_fmac_f32_e32 v21, v20, v20
	v_add_f32_e32 v18, v19, v21
	v_cndmask_b32_e64 v17, v9, v11, s[6:7]
	v_mul_f32_e32 v19, v23, v23
	v_mul_f32_e32 v20, v25, v25
	v_fmac_f32_e32 v19, v22, v22
	v_fmac_f32_e32 v20, v24, v24
	v_add_f32_e32 v19, v19, v20
	v_add_f32_e32 v18, v18, v19
	v_mul_f32_e32 v19, v27, v27
	v_mul_f32_e32 v20, v29, v29
	v_fmac_f32_e32 v19, v26, v26
	v_fmac_f32_e32 v20, v28, v28
	v_add_f32_e32 v19, v19, v20
	v_add_f32_e32 v18, v18, v19
	v_mul_f32_e32 v19, v31, v31
	v_mul_f32_e32 v20, v33, v33
	v_fmac_f32_e32 v19, v30, v30
	v_fmac_f32_e32 v20, v32, v32
	v_add_f32_e32 v19, v19, v20
	v_add_f32_e32 v18, v18, v19
	v_mul_f32_e32 v19, v35, v35
	v_mul_f32_e32 v20, v37, v37
	v_fmac_f32_e32 v19, v34, v34
	v_fmac_f32_e32 v20, v36, v36
	v_add_f32_e32 v19, v19, v20
	v_add_f32_e32 v18, v18, v19
	v_mul_f32_e32 v19, v39, v39
	v_mul_f32_e32 v20, v41, v41
	v_fmac_f32_e32 v19, v38, v38
	v_fmac_f32_e32 v20, v40, v40
	v_add_f32_e32 v19, v19, v20
	v_add_f32_e32 v18, v18, v19
	v_mul_f32_e32 v19, v43, v43
	v_mul_f32_e32 v20, v45, v45
	v_fmac_f32_e32 v19, v42, v42
	v_fmac_f32_e32 v20, v44, v44
	v_add_f32_e32 v19, v19, v20
	v_add_f32_e32 v18, v18, v19
	v_mul_f32_e32 v19, v47, v47
	v_mul_f32_e32 v20, v49, v49
	v_fmac_f32_e32 v19, v46, v46
	v_fmac_f32_e32 v20, v48, v48
	v_add_f32_e32 v19, v19, v20
	v_lshlrev_b32_e32 v17, 2, v17
	v_add_f32_e32 v18, v18, v19
	ds_bpermute_b32 v17, v17, v18
	v_cmp_lt_i32_e64 s[6:7], v12, v10
	v_cvt_pk_bf16_f32 v20, v46, v47
	v_cvt_pk_bf16_f32 v21, v48, v49
	global_store_dwordx2 v[50:51], v[20:21], off offset:3584 sc1
	s_waitcnt lgkmcnt(0)
	v_add_f32_e32 v17, v18, v17
	v_cndmask_b32_e64 v19, v9, v12, s[6:7]
	v_lshlrev_b32_e32 v19, 2, v19
	ds_bpermute_b32 v18, v19, v17
	v_cmp_lt_i32_e64 s[6:7], v13, v10
	s_waitcnt lgkmcnt(0)
	v_add_f32_e32 v17, v17, v18
	v_cndmask_b32_e64 v19, v9, v13, s[6:7]
	v_lshlrev_b32_e32 v19, 2, v19
	ds_bpermute_b32 v18, v19, v17
	v_cmp_lt_i32_e64 s[6:7], v14, v10
	s_waitcnt lgkmcnt(0)
	v_add_f32_e32 v17, v17, v18
	v_cndmask_b32_e64 v19, v9, v14, s[6:7]
	v_lshlrev_b32_e32 v19, 2, v19
	ds_bpermute_b32 v18, v19, v17
	v_cmp_lt_i32_e64 s[6:7], v15, v10
	s_waitcnt lgkmcnt(0)
	v_add_f32_e32 v17, v17, v18
	v_cndmask_b32_e64 v19, v9, v15, s[6:7]
	v_lshlrev_b32_e32 v19, 2, v19
	ds_bpermute_b32 v18, v19, v17
	v_cmp_lt_i32_e64 s[6:7], v16, v10
	s_waitcnt lgkmcnt(0)
	v_add_f32_e32 v17, v17, v18
	v_cndmask_b32_e64 v19, v9, v16, s[6:7]
	v_lshlrev_b32_e32 v18, 2, v19
	ds_bpermute_b32 v18, v18, v17
	s_and_saveexec_b64 s[6:7], vcc
	s_cbranch_execz .LBB0_55
	s_waitcnt lgkmcnt(0)
	v_add_f32_e32 v17, v17, v18
	v_cndmask_b32_e64 v17, 0, v17, s[4:5]
	v_lshl_add_u64 v[18:19], s[92:93], 0, v[2:3]
	global_store_dword v[18:19], v17, off
	s_branch .LBB0_55
